# v29: P10 fused final-norm row-sum exchange via 8-byte {partial,tag} write-through stores polled directly (no ack wait, counter, inv)
# baseline (speedup 1.0000x reference)
; #define LAS __attribute__((address_space(3)))
; __device__ __forceinline__ void xchg_rstd(float mine, LAS float* S, int nrows, float* slots, int myslot, int nslots, unsigned* cnt, unsigned need) {
;     const int tid = threadIdx.x;
;     if (tid < nrows) __hip_atomic_store((unsigned*)(slots + (size_t)tid * 16 + myslot), __float_as_uint(mine), __ATOMIC_RELAXED, __HIP_MEMORY_SCOPE_AGENT);
;     asm volatile("s_waitcnt vmcnt(0)" ::: "memory");
;     __syncthreads();
;     if (tid < 64) {
;         if (tid == 0) (void)__hip_atomic_fetch_add(cnt, 1u, __ATOMIC_RELAXED, __HIP_MEMORY_SCOPE_AGENT);
;         unsigned sp = 0;
;         while ((unsigned)__builtin_amdgcn_readfirstlane(__hip_atomic_load(cnt, __ATOMIC_RELAXED, __HIP_MEMORY_SCOPE_AGENT)) < need) { __builtin_amdgcn_s_sleep(2); if (++sp > XC_SPIN_CAP) break; }
;         __builtin_amdgcn_fence(__ATOMIC_ACQUIRE, "agent");
;         asm volatile("s_waitcnt vmcnt(0)" ::: "memory");
;     }
;     __syncthreads();
;     if (tid < nrows) {
;         float t = 0.f;
;         for (int j = 0; j < nslots; ++j) t += __uint_as_float(__hip_atomic_load((unsigned*)(slots + (size_t)tid * 16 + j), __ATOMIC_RELAXED, __HIP_MEMORY_SCOPE_AGENT));
;         S[tid] = __builtin_amdgcn_rsqf(t * (1.0f / D) + EPS);
;     }
;     __syncthreads();
;     __device__ __forceinline__ void fused(Acc& acc, const Unit& u, int wr, int wc, int fr, int fq, LAS unsigned char* lds) const {
;     ...
;         xchg_rstd(mine, S, 256, slots + (size_t)u.pm * BM * 16, u.pn, 4, cnt + 64 * u.pm, 4u);
.LBB0_1912:
	s_or_b64 exec, exec, s[6:7]
	s_ashr_i32 s11, s10, 31
	s_lshl_b64 s[6:7], s[10:11], 14
	s_add_u32 s6, s20, s6
	s_addc_u32 s7, s21, s7
	v_lshlrev_b32_e32 v2, 2, v130
	s_and_saveexec_b64 s[8:9], s[0:1]
	s_cbranch_execz .LBB0_1929
	v_mov_b32_e32 v5, 0x3c6ef372
	s_lshl_b32 s3, s12, 3
	v_add_u32_e32 v6, s3, v2
	global_store_dwordx2 v6, v[4:5], s[6:7] sc1
	s_mov_b32 s3, 0x100000
.Lxq_poll:
	global_load_dwordx4 v[6:9], v2, s[6:7] sc1
	global_load_dwordx4 v[10:13], v2, s[6:7] offset:16 sc1
	s_waitcnt vmcnt(0)
	v_xor_b32_e32 v14, v5, v7
	v_xor_b32_e32 v15, v5, v9
	v_xor_b32_e32 v16, v5, v11
	v_xor_b32_e32 v17, v5, v13
	v_or3_b32 v14, v14, v15, v16
	v_or_b32_e32 v14, v14, v17
	v_cmp_ne_u32_e32 vcc, 0, v14
	s_cbranch_vccz .Lxq_ready
	s_sleep 1
	s_sub_u32 s3, s3, 1
	s_cmp_lg_u32 s3, 0
	s_cbranch_scc1 .Lxq_poll
.Lxq_ready:
	v_add_f32_e32 v3, 0, v6
	v_add_f32_e32 v3, v3, v8
	v_add_f32_e32 v3, v3, v10
	v_add_f32_e32 v2, v3, v12
	v_mov_b32_e32 v3, 0x358637bd
	v_fmac_f32_e32 v3, 0x3a800000, v2
	v_rsq_f32_e32 v2, v3
	ds_write_b32 v1, v2 offset:4096
